# band tile step: QK and PV blocks with ring-buffered LDS fragment reads + counted lgkmcnt (v2 + this)
# speedup vs baseline: 1.0293x; 1.0085x over previous
; __device__ __forceinline__ f32x4 mfma16(bf16x8 a, bf16x8 b, f32x4 c) { return __builtin_amdgcn_mfma_f32_16x16x32_bf16(a, b, c, 0, 0, 0); }
; __device__ __forceinline__ void b_item(const Params& P, int layer, LAS unsigned char* lds, int item, int tid) {
;     ...
;                 mt = fmaxf(mt, __shfl_xor(mt, 16)); mt = fmaxf(mt, __shfl_xor(mt, 32));
;                 const float mn = fmaxf(mrun[u], mt); alpha[u] = __expf(mrun[u] - mn); mrun[u] = mn;
;                 float ls = 0.f;
; #pragma unroll
;                 for (int sb = 0; sb < 4; ++sb)
; #pragma unroll
;                     for (int r = 0; r < 4; ++r) { const float pe = __expf(accs[u][sb][r] - mn); accs[u][sb][r] = pe; ls += pe; }
;                 lrun[u] = lrun[u] * alpha[u] + ls;
;                 pf[u][0] = pack8(accs[u][0], accs[u][1]); pf[u][1] = pack8(accs[u][2], accs[u][3]); }
;             __builtin_amdgcn_s_setprio(1);
; #pragma unroll
;             for (int vb = 0; vb < 8; ++vb) { acco[0][vb] = acco[0][vb] * alpha[0]; acco[1][vb] = acco[1][vb] * alpha[1];
; #pragma unroll
;                 for (int ks = 0; ks < 2; ++ks) { const bf16x8 vf = tr_frag_a<true>(Vt, vaddr[vb], ks);
;                     acco[0][vb] = mfma16(vf, pf[0][ks], acco[0][vb]); acco[1][vb] = mfma16(vf, pf[1][ks], acco[1][vb]); } }
.LBB0_159:
	s_or_b64 exec, exec, s[0:1]
	s_waitcnt lgkmcnt(0)
	v_max3_f32 v81, v227, v80, v81
	v_sub_f32_e32 v69, v92, v81
	v_mul_f32_e32 v69, 0x3fb8aa3b, v69
	v_exp_f32_e32 v70, v69
	v_sub_f32_e32 v69, v93, v81
	v_mul_f32_e32 v69, 0x3fb8aa3b, v69
	v_exp_f32_e32 v71, v69
	v_sub_f32_e32 v69, v94, v81
	v_sub_f32_e32 v64, v227, v81
	v_mul_f32_e32 v69, 0x3fb8aa3b, v69
	v_mul_f32_e32 v64, 0x3fb8aa3b, v64
	v_exp_f32_e32 v92, v69
	v_sub_f32_e32 v69, v95, v81
	v_exp_f32_e32 v80, v64
	v_sub_f32_e32 v64, v164, v81
	v_mul_f32_e32 v69, 0x3fb8aa3b, v69
	v_mul_f32_e32 v64, 0x3fb8aa3b, v64
	v_sub_f32_e32 v65, v165, v81
	v_exp_f32_e32 v93, v69
	v_sub_f32_e32 v69, v88, v81
	v_exp_f32_e32 v64, v64
	v_mul_f32_e32 v65, 0x3fb8aa3b, v65
	v_sub_f32_e32 v66, v166, v81
	v_mul_f32_e32 v69, 0x3fb8aa3b, v69
	v_exp_f32_e32 v65, v65
	v_mul_f32_e32 v66, 0x3fb8aa3b, v66
	v_sub_f32_e32 v67, v167, v81
	v_exp_f32_e32 v88, v69
	v_sub_f32_e32 v69, v89, v81
	v_exp_f32_e32 v66, v66
	v_mul_f32_e32 v67, 0x3fb8aa3b, v67
	v_mul_f32_e32 v69, 0x3fb8aa3b, v69
	v_exp_f32_e32 v67, v67
	v_exp_f32_e32 v89, v69
	v_sub_f32_e32 v69, v90, v81
	v_add_f32_e32 v68, 0, v64
	v_mul_f32_e32 v69, 0x3fb8aa3b, v69
	v_add_f32_e32 v68, v65, v68
	v_exp_f32_e32 v90, v69
	v_sub_f32_e32 v69, v91, v81
	v_add_f32_e32 v68, v66, v68
	v_mul_f32_e32 v69, 0x3fb8aa3b, v69
	v_add_f32_e32 v68, v67, v68
	v_exp_f32_e32 v91, v69
	v_sub_f32_e32 v69, v84, v81
	v_add_f32_e32 v68, v70, v68
	v_mul_f32_e32 v69, 0x3fb8aa3b, v69
	v_add_f32_e32 v68, v71, v68
	v_exp_f32_e32 v84, v69
	v_sub_f32_e32 v69, v85, v81
	v_add_f32_e32 v68, v92, v68
	v_mul_f32_e32 v69, 0x3fb8aa3b, v69
	v_add_f32_e32 v68, v93, v68
	v_exp_f32_e32 v85, v69
	v_sub_f32_e32 v69, v86, v81
	v_add_f32_e32 v68, v88, v68
	v_mul_f32_e32 v69, 0x3fb8aa3b, v69
	v_add_f32_e32 v68, v89, v68
	v_exp_f32_e32 v86, v69
	v_sub_f32_e32 v69, v87, v81
	v_add_f32_e32 v68, v90, v68
	v_mul_f32_e32 v69, 0x3fb8aa3b, v69
	ds_bpermute_b32 v82, v82, v229
	v_add_f32_e32 v68, v91, v68
	v_exp_f32_e32 v87, v69
	v_add_f32_e32 v68, v84, v68
	v_add_f32_e32 v68, v85, v68
	v_add_f32_e32 v68, v86, v68
	v_add_f32_e32 v83, v87, v68
	v_cvt_pk_bf16_f32 v68, v64, v65
	s_waitcnt lgkmcnt(0)
	v_max_f32_e32 v64, v82, v82
	v_max_f32_e32 v65, v229, v229
	v_max_f32_e32 v82, v65, v64
	v_cvt_pk_bf16_f32 v70, v70, v71
	v_cvt_pk_bf16_f32 v71, v92, v93
	ds_bpermute_b32 v92, v228, v82
	v_cvt_pk_bf16_f32 v69, v66, v67
	v_cvt_pk_bf16_f32 v66, v84, v85
	v_cvt_pk_bf16_f32 v67, v86, v87
	v_cvt_pk_bf16_f32 v64, v88, v89
	s_waitcnt lgkmcnt(0)
	v_max3_f32 v84, v226, v82, v92
	v_sub_f32_e32 v85, v168, v84
	v_mul_f32_e32 v85, 0x3fb8aa3b, v85
	v_exp_f32_e32 v86, v85
	v_sub_f32_e32 v85, v169, v84
	v_mul_f32_e32 v85, 0x3fb8aa3b, v85
	v_exp_f32_e32 v87, v85
	v_sub_f32_e32 v85, v170, v84
	v_sub_f32_e32 v76, v76, v84
	v_mul_f32_e32 v85, 0x3fb8aa3b, v85
	v_mul_f32_e32 v76, 0x3fb8aa3b, v76
	v_cvt_pk_bf16_f32 v65, v90, v91
	v_exp_f32_e32 v88, v85
	v_sub_f32_e32 v85, v171, v84
	v_exp_f32_e32 v90, v76
	v_sub_f32_e32 v76, v77, v84
	v_mul_f32_e32 v85, 0x3fb8aa3b, v85
	v_mul_f32_e32 v76, 0x3fb8aa3b, v76
	v_exp_f32_e32 v89, v85
	v_exp_f32_e32 v91, v76
	v_sub_f32_e32 v76, v78, v84
	v_add_f32_e32 v85, 0, v86
	v_mul_f32_e32 v76, 0x3fb8aa3b, v76
	v_add_f32_e32 v85, v87, v85
	v_exp_f32_e32 v92, v76
	v_sub_f32_e32 v76, v79, v84
	v_add_f32_e32 v85, v88, v85
	v_mul_f32_e32 v76, 0x3fb8aa3b, v76
	v_sub_f32_e32 v72, v72, v84
	v_add_f32_e32 v85, v89, v85
	v_exp_f32_e32 v79, v76
	v_mul_f32_e32 v72, 0x3fb8aa3b, v72
	v_sub_f32_e32 v73, v73, v84
	v_sub_f32_e32 v77, v172, v84
	v_add_f32_e32 v76, v90, v85
	v_exp_f32_e32 v72, v72
	v_mul_f32_e32 v73, 0x3fb8aa3b, v73
	v_sub_f32_e32 v74, v74, v84
	v_mul_f32_e32 v77, 0x3fb8aa3b, v77
	v_add_f32_e32 v76, v91, v76
	v_exp_f32_e32 v73, v73
	v_mul_f32_e32 v74, 0x3fb8aa3b, v74
	v_sub_f32_e32 v75, v75, v84
	v_exp_f32_e32 v93, v77
	v_sub_f32_e32 v77, v173, v84
	v_add_f32_e32 v76, v92, v76
	v_exp_f32_e32 v74, v74
	v_mul_f32_e32 v75, 0x3fb8aa3b, v75
	v_mul_f32_e32 v77, 0x3fb8aa3b, v77
	v_add_f32_e32 v76, v79, v76
	v_exp_f32_e32 v75, v75
	v_exp_f32_e32 v94, v77
	v_sub_f32_e32 v77, v174, v84
	v_add_f32_e32 v76, v72, v76
	v_mul_f32_e32 v77, 0x3fb8aa3b, v77
	v_add_f32_e32 v76, v73, v76
	v_exp_f32_e32 v95, v77
	v_sub_f32_e32 v77, v175, v84
	v_sub_f32_e32 v82, v226, v84
	v_add_f32_e32 v76, v74, v76
	v_mul_f32_e32 v77, 0x3fb8aa3b, v77
	v_mul_f32_e32 v82, 0x3fb8aa3b, v82
	v_add_f32_e32 v76, v75, v76
	v_exp_f32_e32 v164, v77
	v_exp_f32_e32 v82, v82
	v_add_f32_e32 v76, v93, v76
	v_add_f32_e32 v76, v94, v76
	v_add_f32_e32 v76, v95, v76
	v_add_f32_e32 v85, v164, v76
	v_fmac_f32_e32 v83, v225, v80
	v_fmac_f32_e32 v85, v224, v82
	v_cvt_pk_bf16_f32 v76, v86, v87
	v_cvt_pk_bf16_f32 v77, v88, v89
	v_cvt_pk_bf16_f32 v78, v90, v91
	v_cvt_pk_bf16_f32 v79, v92, v79
	v_cvt_pk_bf16_f32 v72, v72, v73
	v_cvt_pk_bf16_f32 v73, v74, v75
	v_cvt_pk_bf16_f32 v74, v93, v94
	v_cvt_pk_bf16_f32 v75, v95, v164
	s_setprio 1
	v_add3_u32 v240, s28, v198, v197
	ds_read_b64_tr_b16 v[164:165], v240 offset:16384
	ds_read_b64_tr_b16 v[166:167], v240 offset:20480
	ds_read_b64_tr_b16 v[168:169], v240 offset:24576
	ds_read_b64_tr_b16 v[170:171], v240 offset:28672
	v_add3_u32 v241, s28, v199, v197
	ds_read_b64_tr_b16 v[172:173], v241 offset:16384
	ds_read_b64_tr_b16 v[174:175], v241 offset:20480
	v_pk_mul_f32 v[60:61], v[60:61], v[80:81] op_sel_hi:[1,0]
	v_pk_mul_f32 v[62:63], v[62:63], v[80:81] op_sel_hi:[1,0]
	v_pk_mul_f32 v[28:29], v[28:29], v[82:83] op_sel_hi:[1,0]
	v_pk_mul_f32 v[30:31], v[30:31], v[82:83] op_sel_hi:[1,0]
	s_waitcnt lgkmcnt(4)
; __device__ __forceinline__ f32x4 mfma16(bf16x8 a, bf16x8 b, f32x4 c) { return __builtin_amdgcn_mfma_f32_16x16x32_bf16(a, b, c, 0, 0, 0); }
; __device__ __forceinline__ void b_item(const Params& P, int layer, LAS unsigned char* lds, int item, int tid) {
;     ...
;             __builtin_amdgcn_s_setprio(1);
; #pragma unroll
;             for (int vb = 0; vb < 8; ++vb) { acco[0][vb] = acco[0][vb] * alpha[0]; acco[1][vb] = acco[1][vb] * alpha[1];
; #pragma unroll
;                 for (int ks = 0; ks < 2; ++ks) { const bf16x8 vf = tr_frag_a<true>(Vt, vaddr[vb], ks);
;                     acco[0][vb] = mfma16(vf, pf[0][ks], acco[0][vb]); acco[1][vb] = mfma16(vf, pf[1][ks], acco[1][vb]); } }
;             __builtin_amdgcn_s_setprio(0);
	v_mfma_f32_16x16x32_bf16 v[60:63], v[164:167], v[68:71], v[60:63]
	v_mfma_f32_16x16x32_bf16 v[28:31], v[164:167], v[76:79], v[28:31]
	ds_read_b64_tr_b16 v[236:237], v241 offset:24576
	ds_read_b64_tr_b16 v[238:239], v241 offset:28672
	v_pk_mul_f32 v[56:57], v[56:57], v[80:81] op_sel_hi:[1,0]
	v_pk_mul_f32 v[58:59], v[58:59], v[80:81] op_sel_hi:[1,0]
	v_pk_mul_f32 v[24:25], v[24:25], v[82:83] op_sel_hi:[1,0]
	v_pk_mul_f32 v[26:27], v[26:27], v[82:83] op_sel_hi:[1,0]
	s_waitcnt lgkmcnt(4)
	v_mfma_f32_16x16x32_bf16 v[60:63], v[168:171], v[64:67], v[60:63]
	v_mfma_f32_16x16x32_bf16 v[28:31], v[168:171], v[72:75], v[28:31]
	v_add3_u32 v240, s28, v200, v197
	ds_read_b64_tr_b16 v[164:165], v240 offset:16384
	ds_read_b64_tr_b16 v[166:167], v240 offset:20480
	s_waitcnt lgkmcnt(4)
	v_mfma_f32_16x16x32_bf16 v[56:59], v[172:175], v[68:71], v[56:59]
	v_mfma_f32_16x16x32_bf16 v[24:27], v[172:175], v[76:79], v[24:27]
	ds_read_b64_tr_b16 v[168:169], v240 offset:24576
	ds_read_b64_tr_b16 v[170:171], v240 offset:28672
	v_pk_mul_f32 v[52:53], v[52:53], v[80:81] op_sel_hi:[1,0]
	v_pk_mul_f32 v[54:55], v[54:55], v[80:81] op_sel_hi:[1,0]
	v_pk_mul_f32 v[20:21], v[20:21], v[82:83] op_sel_hi:[1,0]
	v_pk_mul_f32 v[22:23], v[22:23], v[82:83] op_sel_hi:[1,0]
	s_waitcnt lgkmcnt(4)
	v_mfma_f32_16x16x32_bf16 v[56:59], v[236:239], v[64:67], v[56:59]
	v_mfma_f32_16x16x32_bf16 v[24:27], v[236:239], v[72:75], v[24:27]
	v_add3_u32 v241, s28, v201, v197
	ds_read_b64_tr_b16 v[172:173], v241 offset:16384
	ds_read_b64_tr_b16 v[174:175], v241 offset:20480
	s_waitcnt lgkmcnt(4)
	v_mfma_f32_16x16x32_bf16 v[52:55], v[164:167], v[68:71], v[52:55]
	v_mfma_f32_16x16x32_bf16 v[20:23], v[164:167], v[76:79], v[20:23]
	ds_read_b64_tr_b16 v[236:237], v241 offset:24576
	ds_read_b64_tr_b16 v[238:239], v241 offset:28672
	v_pk_mul_f32 v[48:49], v[48:49], v[80:81] op_sel_hi:[1,0]
	v_pk_mul_f32 v[50:51], v[50:51], v[80:81] op_sel_hi:[1,0]
	v_pk_mul_f32 v[16:17], v[16:17], v[82:83] op_sel_hi:[1,0]
	v_pk_mul_f32 v[18:19], v[18:19], v[82:83] op_sel_hi:[1,0]
	s_waitcnt lgkmcnt(4)
	v_mfma_f32_16x16x32_bf16 v[52:55], v[168:171], v[64:67], v[52:55]
	v_mfma_f32_16x16x32_bf16 v[20:23], v[168:171], v[72:75], v[20:23]
	v_add3_u32 v240, s28, v202, v197
	ds_read_b64_tr_b16 v[164:165], v240 offset:16384
	ds_read_b64_tr_b16 v[166:167], v240 offset:20480
	s_waitcnt lgkmcnt(4)
	v_mfma_f32_16x16x32_bf16 v[48:51], v[172:175], v[68:71], v[48:51]
	v_mfma_f32_16x16x32_bf16 v[16:19], v[172:175], v[76:79], v[16:19]
	ds_read_b64_tr_b16 v[168:169], v240 offset:24576
	ds_read_b64_tr_b16 v[170:171], v240 offset:28672
	v_pk_mul_f32 v[44:45], v[44:45], v[80:81] op_sel_hi:[1,0]
	v_pk_mul_f32 v[46:47], v[46:47], v[80:81] op_sel_hi:[1,0]
	v_pk_mul_f32 v[12:13], v[12:13], v[82:83] op_sel_hi:[1,0]
	v_pk_mul_f32 v[14:15], v[14:15], v[82:83] op_sel_hi:[1,0]
	s_waitcnt lgkmcnt(4)
	v_mfma_f32_16x16x32_bf16 v[48:51], v[236:239], v[64:67], v[48:51]
	v_mfma_f32_16x16x32_bf16 v[16:19], v[236:239], v[72:75], v[16:19]
	v_add3_u32 v241, s28, v203, v197
	ds_read_b64_tr_b16 v[172:173], v241 offset:16384
	ds_read_b64_tr_b16 v[174:175], v241 offset:20480
	s_waitcnt lgkmcnt(4)
	v_mfma_f32_16x16x32_bf16 v[44:47], v[164:167], v[68:71], v[44:47]
	v_mfma_f32_16x16x32_bf16 v[12:15], v[164:167], v[76:79], v[12:15]
	ds_read_b64_tr_b16 v[236:237], v241 offset:24576
	ds_read_b64_tr_b16 v[238:239], v241 offset:28672
	v_pk_mul_f32 v[40:41], v[40:41], v[80:81] op_sel_hi:[1,0]
	v_pk_mul_f32 v[42:43], v[42:43], v[80:81] op_sel_hi:[1,0]
	v_pk_mul_f32 v[8:9], v[8:9], v[82:83] op_sel_hi:[1,0]
	v_pk_mul_f32 v[10:11], v[10:11], v[82:83] op_sel_hi:[1,0]
	s_waitcnt lgkmcnt(4)
	v_mfma_f32_16x16x32_bf16 v[44:47], v[168:171], v[64:67], v[44:47]
	v_mfma_f32_16x16x32_bf16 v[12:15], v[168:171], v[72:75], v[12:15]
	v_add3_u32 v240, s28, v204, v197
	ds_read_b64_tr_b16 v[164:165], v240 offset:16384
	ds_read_b64_tr_b16 v[166:167], v240 offset:20480
	s_waitcnt lgkmcnt(4)
	v_mfma_f32_16x16x32_bf16 v[40:43], v[172:175], v[68:71], v[40:43]
	v_mfma_f32_16x16x32_bf16 v[8:11], v[172:175], v[76:79], v[8:11]
	ds_read_b64_tr_b16 v[168:169], v240 offset:24576
	ds_read_b64_tr_b16 v[170:171], v240 offset:28672
	v_pk_mul_f32 v[36:37], v[36:37], v[80:81] op_sel_hi:[1,0]
	v_pk_mul_f32 v[38:39], v[38:39], v[80:81] op_sel_hi:[1,0]
	v_pk_mul_f32 v[4:5], v[4:5], v[82:83] op_sel_hi:[1,0]
	v_pk_mul_f32 v[6:7], v[6:7], v[82:83] op_sel_hi:[1,0]
	s_waitcnt lgkmcnt(4)
	v_mfma_f32_16x16x32_bf16 v[40:43], v[236:239], v[64:67], v[40:43]
	v_mfma_f32_16x16x32_bf16 v[8:11], v[236:239], v[72:75], v[8:11]
	v_add3_u32 v241, s28, v205, v197
	ds_read_b64_tr_b16 v[172:173], v241 offset:16384
	ds_read_b64_tr_b16 v[174:175], v241 offset:20480
	s_waitcnt lgkmcnt(4)
	v_mfma_f32_16x16x32_bf16 v[36:39], v[164:167], v[68:71], v[36:39]
	v_mfma_f32_16x16x32_bf16 v[4:7], v[164:167], v[76:79], v[4:7]
	ds_read_b64_tr_b16 v[236:237], v241 offset:24576
	ds_read_b64_tr_b16 v[238:239], v241 offset:28672
	v_pk_mul_f32 v[32:33], v[32:33], v[80:81] op_sel_hi:[1,0]
	v_pk_mul_f32 v[34:35], v[34:35], v[80:81] op_sel_hi:[1,0]
	v_pk_mul_f32 v[0:1], v[0:1], v[82:83] op_sel_hi:[1,0]
	v_pk_mul_f32 v[2:3], v[2:3], v[82:83] op_sel_hi:[1,0]
	s_waitcnt lgkmcnt(4)
	v_mfma_f32_16x16x32_bf16 v[36:39], v[168:171], v[64:67], v[36:39]
	v_mfma_f32_16x16x32_bf16 v[4:7], v[168:171], v[72:75], v[4:7]
	s_waitcnt lgkmcnt(2)
	v_mfma_f32_16x16x32_bf16 v[32:35], v[172:175], v[68:71], v[32:35]
	v_mfma_f32_16x16x32_bf16 v[0:3], v[172:175], v[76:79], v[0:3]
	s_waitcnt lgkmcnt(0)
	v_mfma_f32_16x16x32_bf16 v[32:35], v[236:239], v[64:67], v[32:35]
	v_mfma_f32_16x16x32_bf16 v[0:3], v[236:239], v[72:75], v[0:3]
	s_setprio 0
	v_mov_b32_e32 v227, v81
	v_mov_b32_e32 v226, v84
	v_mov_b32_e32 v224, v85
	v_mov_b32_e32 v225, v83

; __device__ __forceinline__ f32x4 mfma16(bf16x8 a, bf16x8 b, f32x4 c) { return __builtin_amdgcn_mfma_f32_16x16x32_bf16(a, b, c, 0, 0, 0); }
; __device__ __forceinline__ void b_item(const Params& P, int layer, LAS unsigned char* lds, int item, int tid) {
;     ...
;         const bool active = (j >= qc) && (j <= qc + 8);
;         if (active) {
;             const int dl = 64 * (8 + qc - j);
;             f32x4 accs[2][4];
; #pragma unroll
;             for (int sb = 0; sb < 4; ++sb) { accs[0][sb] = (f32x4){0.f, 0.f, 0.f, 0.f}; accs[1][sb] = (f32x4){0.f, 0.f, 0.f, 0.f}; }
;             __builtin_amdgcn_s_setprio(1);
; #pragma unroll
;             for (int kk = 0; kk < 4; ++kk) { const bf16x8 q0 = row_frag_a(Qw, kaddr[kk], 0), q1 = row_frag_a(Qw, kaddr[kk], 1);
; #pragma unroll
;                 for (int sb = 0; sb < 4; ++sb) { const bf16x8 kf = row_frag_a(Kt, kaddr[kk], sb);
;                     accs[0][sb] = mfma16(kf, q0, accs[0][sb]); accs[1][sb] = mfma16(kf, q1, accs[1][sb]); } }
.LBB0_163:
	s_add_i32 s57, s57, 1
	v_cmp_ge_i32_e32 vcc, s57, v191
	v_cmp_le_i32_e64 s[0:1], s57, v207
	s_and_b64 s[0:1], vcc, s[0:1]
	s_and_saveexec_b64 s[14:15], s[0:1]
	s_cbranch_execz .LBB0_160
	s_add_i32 s28, s28, 0
	s_add_i32 s28, s28, 0x10000
	s_setprio 1
	v_add_u32_e32 v244, v206, v193
	v_add_u32_e32 v245, s28, v193
	ds_read_b128 v[164:167], v244
	ds_read_b128 v[168:171], v244 offset:4096
	ds_read_b128 v[236:239], v245
	ds_read_b128 v[240:243], v245 offset:4096
	ds_read_b128 v[252:255], v245 offset:8192
	s_waitcnt lgkmcnt(2)
	v_mfma_f32_16x16x32_bf16 v[92:95], v[236:239], v[164:167], 0
	v_mfma_f32_16x16x32_bf16 v[76:79], v[236:239], v[168:171], 0
	ds_read_b128 v[236:239], v245 offset:12288
	v_add_u32_e32 v244, v206, v194
	ds_read_b128 v[172:175], v244
	ds_read_b128 v[228:231], v244 offset:4096
	s_waitcnt lgkmcnt(4)
	v_mfma_f32_16x16x32_bf16 v[88:91], v[240:243], v[164:167], 0
	v_mfma_f32_16x16x32_bf16 v[72:75], v[240:243], v[168:171], 0
	v_add_u32_e32 v245, s28, v194
	ds_read_b128 v[240:243], v245
	s_waitcnt lgkmcnt(4)
	v_mfma_f32_16x16x32_bf16 v[84:87], v[252:255], v[164:167], 0
	v_mfma_f32_16x16x32_bf16 v[68:71], v[252:255], v[168:171], 0
	ds_read_b128 v[252:255], v245 offset:4096
	s_waitcnt lgkmcnt(4)
	v_mfma_f32_16x16x32_bf16 v[80:83], v[236:239], v[164:167], 0
	v_mfma_f32_16x16x32_bf16 v[64:67], v[236:239], v[168:171], 0
	ds_read_b128 v[236:239], v245 offset:8192
	s_waitcnt lgkmcnt(2)
	v_mfma_f32_16x16x32_bf16 v[92:95], v[240:243], v[172:175], v[92:95]
	v_mfma_f32_16x16x32_bf16 v[76:79], v[240:243], v[228:231], v[76:79]
	ds_read_b128 v[240:243], v245 offset:12288
	v_add_u32_e32 v244, v206, v195
	ds_read_b128 v[164:167], v244
	ds_read_b128 v[168:171], v244 offset:4096
	s_waitcnt lgkmcnt(4)
	v_mfma_f32_16x16x32_bf16 v[88:91], v[252:255], v[172:175], v[88:91]
	v_mfma_f32_16x16x32_bf16 v[72:75], v[252:255], v[228:231], v[72:75]
	v_add_u32_e32 v245, s28, v195
	ds_read_b128 v[252:255], v245
	s_waitcnt lgkmcnt(4)
	v_mfma_f32_16x16x32_bf16 v[84:87], v[236:239], v[172:175], v[84:87]
	v_mfma_f32_16x16x32_bf16 v[68:71], v[236:239], v[228:231], v[68:71]
	ds_read_b128 v[236:239], v245 offset:4096
	s_waitcnt lgkmcnt(4)
	v_mfma_f32_16x16x32_bf16 v[80:83], v[240:243], v[172:175], v[80:83]
	v_mfma_f32_16x16x32_bf16 v[64:67], v[240:243], v[228:231], v[64:67]
	ds_read_b128 v[240:243], v245 offset:8192
	s_waitcnt lgkmcnt(2)
	v_mfma_f32_16x16x32_bf16 v[92:95], v[252:255], v[164:167], v[92:95]
	v_mfma_f32_16x16x32_bf16 v[76:79], v[252:255], v[168:171], v[76:79]
	ds_read_b128 v[252:255], v245 offset:12288
	v_add_u32_e32 v244, v206, v196
	ds_read_b128 v[172:175], v244
	ds_read_b128 v[228:231], v244 offset:4096
	s_waitcnt lgkmcnt(4)
	v_mfma_f32_16x16x32_bf16 v[88:91], v[236:239], v[164:167], v[88:91]
	v_mfma_f32_16x16x32_bf16 v[72:75], v[236:239], v[168:171], v[72:75]
	v_add_u32_e32 v245, s28, v196
	ds_read_b128 v[236:239], v245
	s_waitcnt lgkmcnt(4)
	v_mfma_f32_16x16x32_bf16 v[84:87], v[240:243], v[164:167], v[84:87]
	v_mfma_f32_16x16x32_bf16 v[68:71], v[240:243], v[168:171], v[68:71]
	ds_read_b128 v[240:243], v245 offset:4096
	s_waitcnt lgkmcnt(4)
	v_mfma_f32_16x16x32_bf16 v[80:83], v[252:255], v[164:167], v[80:83]
	v_mfma_f32_16x16x32_bf16 v[64:67], v[252:255], v[168:171], v[64:67]
	ds_read_b128 v[252:255], v245 offset:8192
	s_waitcnt lgkmcnt(2)
	v_mfma_f32_16x16x32_bf16 v[92:95], v[236:239], v[172:175], v[92:95]
	v_mfma_f32_16x16x32_bf16 v[76:79], v[236:239], v[228:231], v[76:79]
	ds_read_b128 v[236:239], v245 offset:12288
	s_waitcnt lgkmcnt(2)
	v_mfma_f32_16x16x32_bf16 v[88:91], v[240:243], v[172:175], v[88:91]
	v_mfma_f32_16x16x32_bf16 v[72:75], v[240:243], v[228:231], v[72:75]
	s_waitcnt lgkmcnt(1)
	v_mfma_f32_16x16x32_bf16 v[84:87], v[252:255], v[172:175], v[84:87]
	v_mfma_f32_16x16x32_bf16 v[68:71], v[252:255], v[228:231], v[68:71]
	s_waitcnt lgkmcnt(0)
	v_mfma_f32_16x16x32_bf16 v[80:83], v[236:239], v[172:175], v[80:83]
	v_mfma_f32_16x16x32_bf16 v[64:67], v[236:239], v[228:231], v[64:67]
	s_setprio 0
	v_cmp_gt_i32_e32 vcc, 3, v221
	v_add_u32_e32 v172, v192, v222
	s_and_saveexec_b64 s[0:1], vcc
	s_xor_b64 s[0:1], exec, s[0:1]
	s_cbranch_execz .LBB0_166
	v_add_u32_e32 v166, 0x200, v172
	v_add_u32_e32 v165, 0x1ff, v172
	v_min_i32_e32 v164, 0x80, v166
	v_min_i32_e32 v165, 0x80, v165
	v_lshl_add_u32 v164, v164, 2, s74
	v_lshl_add_u32 v165, v165, 2, s74
	ds_read_b32 v164, v164 offset:512
	ds_read_b32 v165, v165 offset:512
	s_waitcnt lgkmcnt(0)
	v_pk_fma_f32 v[164:165], v[92:93], s[34:35], v[164:165] op_sel_hi:[1,0,1]
	v_min_i32_e32 v92, 0x82, v166
	v_min_i32_e32 v93, 0x83, v166
	v_lshl_add_u32 v92, v92, 2, s74
	v_lshl_add_u32 v93, v93, 2, s74
	ds_read_b32 v92, v92 offset:504
	ds_read_b32 v93, v93 offset:500
	v_max3_f32 v168, v164, s96, v165
	s_waitcnt lgkmcnt(0)
	v_pk_fma_f32 v[166:167], v[94:95], s[34:35], v[92:93] op_sel_hi:[1,0,1]
	s_nop 0
	v_max3_f32 v169, v168, v166, v167
